# rebalance: 7168 instead of 5376 expert-table rows converted in the P3 slack (fewer in P2's idle round)
# speedup vs baseline: 1.0059x; 1.0034x over previous
; __global__ void __launch_bounds__(NTHR, 2) mega(Args args) {
;     ...
;         {
;             const int nslots = G >> 3, rr = 103 % nslots, xcd = (int)blockIdx.x & 7, slot = (int)blockIdx.x >> 3;
;             const bool freewg = rr == 0 || slot >= rr;
;             const int fidx = rr == 0 ? (int)blockIdx.x : (slot - rr) * 8 + xcd, nfree = rr == 0 ? G : (nslots - rr) * 8;
;             if (freewg && rep == 0)
;                 for (int e = fidx * NWAVES + wave; e < 2 * 16384 - CVT_LATE; e += nfree * NWAVES) { if (e < 16384) peer::cvt_row_i4(pu, UT8, SUs, e, lane); else peer::cvt_row_fp4(pv, VT8, SVs, e - 16384, lane); }
.LBB0_458:
	s_ashr_i32 s1, s18, 3
	s_abs_i32 s3, s1
	v_cvt_f32_u32_e32 v1, s3
	s_sub_i32 s4, 0, s3
	s_ashr_i32 s0, s2, 3
	v_rcp_iflag_f32_e32 v1, v1
	s_nop 0
	v_mul_f32_e32 v1, 0x4f7ffffe, v1
	v_cvt_u32_f32_e32 v1, v1
	s_nop 0
	v_readfirstlane_b32 s5, v1
	s_mul_i32 s4, s4, s5
	s_mul_hi_u32 s4, s5, s4
	s_add_i32 s5, s5, s4
	s_mul_hi_u32 s4, s5, 0x67
	s_mul_i32 s4, s4, s3
	s_sub_i32 s4, 0x67, s4
	s_sub_i32 s5, s4, s3
	s_cmp_ge_u32 s4, s3
	s_cselect_b32 s4, s5, s4
	s_sub_i32 s5, s4, s3
	s_cmp_ge_u32 s4, s3
	s_cselect_b32 s6, s5, s4
	s_cmp_eq_u32 s6, 0
	s_cselect_b64 s[4:5], -1, 0
	s_cmp_lg_u32 s6, 0
	s_cselect_b64 s[8:9], -1, 0
	s_cmp_lt_i32 s0, s6
	s_cselect_b64 s[10:11], -1, 0
	s_and_b64 s[8:9], s[8:9], s[10:11]
	s_and_b64 vcc, exec, s[8:9]
	s_cbranch_vccnz .LBB0_472
	s_sub_i32 s0, s0, s6
	s_and_b32 s3, s2, 7
	s_lshl_b32 s0, s0, 3
	s_or_b32 s0, s0, s3
	s_and_b64 s[8:9], s[4:5], exec
	s_cselect_b32 s0, s2, s0
	s_lshl_b32 s3, s0, 3
	s_add_i32 s0, s3, s77
	s_cmpk_gt_i32 s0, 0x63ff
	s_cbranch_scc1 .LBB0_472
	s_sub_i32 s1, s1, s6
	s_lshl_b32 s1, s1, 3
	s_and_b64 s[4:5], s[4:5], exec
	s_cselect_b32 s1, s18, s1
	s_lshl_b32 s10, s1, 3
	s_ashr_i32 s1, s3, 31
	s_add_u32 s34, s77, s3
	v_and_b32_e32 v1, 1, v0
	s_addc_u32 s35, 0, s1
	v_mov_b32_e32 v3, 0
	v_cmp_eq_u32_e64 s[4:5], 0, v1
	v_lshlrev_b32_e32 v1, 10, v0
	s_lshl_b64 s[12:13], s[34:35], 2
	v_and_b32_e32 v6, 0xc000, v1
	v_mov_b32_e32 v7, v3
	s_add_u32 s1, s30, s12
	s_addc_u32 s3, s31, s13
	v_lshl_add_u64 v[10:11], s[34:35], 0, v[6:7]
	v_lshlrev_b32_e32 v1, 3, v0
	s_add_u32 s12, s1, 0x3000000
	v_lshlrev_b64 v[10:11], 7, v[10:11]
	s_movk_i32 s1, 0x78
	v_and_or_b32 v10, v1, s1, v10
	s_addc_u32 s13, s3, 0
	s_ashr_i32 s11, s10, 31
	v_lshl_add_u64 v[10:11], s[30:31], 0, v[10:11]
	s_mov_b64 s[16:17], 0x1000000
	s_lshl_b64 s[14:15], s[10:11], 2
	v_lshl_add_u64 v[10:11], v[10:11], 0, s[16:17]
	s_lshl_b64 s[16:17], s[10:11], 7
	s_lshl_b64 s[34:35], s[34:35], 12
	v_and_b32_e32 v8, 0x70, v1
	s_mov_b64 s[82:83], s[22:23]
	s_add_u32 s22, s22, s34
	v_mbcnt_lo_u32_b32 v1, -1, 0
	v_lshlrev_b32_e32 v2, 6, v178
	s_addc_u32 s23, s23, s35
	v_mbcnt_hi_u32_b32 v1, -1, v1
	v_lshl_add_u64 v[4:5], s[24:25], 0, v[2:3]
	v_mov_b32_e32 v9, v3
	v_lshl_add_u64 v[12:13], s[22:23], 0, v[2:3]
	v_and_b32_e32 v2, 64, v1
	s_mov_b32 s9, 0
	v_lshl_add_u64 v[8:9], s[20:21], 0, v[8:9]
	v_cmp_eq_u32_e64 s[6:7], 0, v178
	v_lshl_add_u64 v[12:13], v[12:13], 0, 32
	s_lshl_b64 s[22:23], s[10:11], 12
	s_mov_b32 s1, 0x40e00000
	s_movk_i32 s3, 0xf0
	s_movk_i32 s11, 0xf00
	s_mov_b32 s19, 0xf0000
	s_mov_b32 s34, 0xf000000
	s_mov_b32 s35, 0xc050c00
	s_mov_b32 s42, 0xf0f0f0f
	s_mov_b32 s43, 0xff00ff
	v_add_u32_e32 v7, 64, v2
	v_xor_b32_e32 v14, 1, v1
	v_xor_b32_e32 v15, 2, v1
	v_xor_b32_e32 v16, 4, v1
	v_xor_b32_e32 v17, 8, v1
	v_xor_b32_e32 v18, 16, v1
	v_xor_b32_e32 v19, 32, v1
	s_lshl_b32 s79, s77, 14
	s_mov_b32 s80, s79
	v_lshlrev_b32_e32 v44, 4, v178
	v_lshlrev_b32_e32 v45, 6, v178
	s_mov_b32 s81, s0
	s_cmpk_lt_i32 s81, 0x6400
	s_cselect_b32 s84, s81, s0
	s_cmpk_lt_i32 s84, 0x4000
	s_cselect_b32 s86, s82, s24
	s_cselect_b32 s87, s83, s25
	s_and_b32 s85, s84, 0x3fff
	s_lshl_b32 s85, s85, 12
	s_add_u32 s86, s86, s85
	s_addc_u32 s87, s87, 0
	s_mov_b32 m0, s80
	s_nop 0
	global_load_lds_dwordx4 v45, s[86:87]
	s_add_i32 m0, s80, 0x3f0
	s_nop 0
	global_load_lds_dwordx4 v45, s[86:87] offset:16
	s_add_i32 m0, s80, 0x7e0
	s_nop 0
	global_load_lds_dwordx4 v45, s[86:87] offset:32
	s_add_i32 m0, s80, 0xbd0
	s_nop 0
	global_load_lds_dwordx4 v45, s[86:87] offset:48
	global_load_dword v47, v45, s[86:87]
	global_load_dword v47, v45, s[86:87]
	s_add_i32 s80, s80, 0x1000
	s_sub_i32 s85, s80, s79
	s_and_b32 s85, s85, 0x3fff
	s_add_i32 s80, s79, s85
	s_add_i32 s81, s81, s10
	s_cmpk_lt_i32 s81, 0x6400
	s_cselect_b32 s84, s81, s0
	s_cmpk_lt_i32 s84, 0x4000
	s_cselect_b32 s86, s82, s24
	s_cselect_b32 s87, s83, s25
	s_and_b32 s85, s84, 0x3fff
	s_lshl_b32 s85, s85, 12
	s_add_u32 s86, s86, s85
	s_addc_u32 s87, s87, 0
	s_mov_b32 m0, s80
	s_nop 0
	global_load_lds_dwordx4 v45, s[86:87]
	s_add_i32 m0, s80, 0x3f0
	s_nop 0
	global_load_lds_dwordx4 v45, s[86:87] offset:16
	s_add_i32 m0, s80, 0x7e0
	s_nop 0
	global_load_lds_dwordx4 v45, s[86:87] offset:32
	s_add_i32 m0, s80, 0xbd0
	s_nop 0
	global_load_lds_dwordx4 v45, s[86:87] offset:48
	global_load_dword v47, v45, s[86:87]
	global_load_dword v47, v45, s[86:87]
	s_add_i32 s80, s80, 0x1000
	s_sub_i32 s85, s80, s79
	s_and_b32 s85, s85, 0x3fff
	s_add_i32 s80, s79, s85
	s_add_i32 s81, s81, s10
	s_cmpk_lt_i32 s81, 0x6400
	s_cselect_b32 s84, s81, s0
	s_cmpk_lt_i32 s84, 0x4000
	s_cselect_b32 s86, s82, s24
	s_cselect_b32 s87, s83, s25
	s_and_b32 s85, s84, 0x3fff
	s_lshl_b32 s85, s85, 12
	s_add_u32 s86, s86, s85
	s_addc_u32 s87, s87, 0
	s_mov_b32 m0, s80
	s_nop 0
	global_load_lds_dwordx4 v45, s[86:87]
	s_add_i32 m0, s80, 0x3f0
	s_nop 0
	global_load_lds_dwordx4 v45, s[86:87] offset:16
	s_add_i32 m0, s80, 0x7e0
	s_nop 0
	global_load_lds_dwordx4 v45, s[86:87] offset:32
	s_add_i32 m0, s80, 0xbd0
	s_nop 0
	global_load_lds_dwordx4 v45, s[86:87] offset:48
	global_load_dword v47, v45, s[86:87]
	global_load_dword v47, v45, s[86:87]
	s_add_i32 s80, s80, 0x1000
	s_sub_i32 s85, s80, s79
	s_and_b32 s85, s85, 0x3fff
	s_add_i32 s80, s79, s85
	s_add_i32 s81, s81, s10
	s_cmpk_lt_i32 s81, 0x6400
	s_cselect_b32 s84, s81, s0
	s_cmpk_lt_i32 s84, 0x4000
	s_cselect_b32 s86, s82, s24
	s_cselect_b32 s87, s83, s25
	s_and_b32 s85, s84, 0x3fff
	s_lshl_b32 s85, s85, 12
	s_add_u32 s86, s86, s85
	s_addc_u32 s87, s87, 0
	s_mov_b32 m0, s80
	s_nop 0
	global_load_lds_dwordx4 v45, s[86:87]
	s_add_i32 m0, s80, 0x3f0
	s_nop 0
	global_load_lds_dwordx4 v45, s[86:87] offset:16
	s_add_i32 m0, s80, 0x7e0
	s_nop 0
	global_load_lds_dwordx4 v45, s[86:87] offset:32
	s_add_i32 m0, s80, 0xbd0
	s_nop 0
	global_load_lds_dwordx4 v45, s[86:87] offset:48
	global_load_dword v47, v45, s[86:87]
	global_load_dword v47, v45, s[86:87]
	s_add_i32 s80, s80, 0x1000
	s_sub_i32 s85, s80, s79
	s_and_b32 s85, s85, 0x3fff
	s_add_i32 s80, s79, s85
	s_add_i32 s81, s81, s10
	s_branch .LBB0_463

; __device__ __forceinline__ unsigned fp4_code(float y) { const int q = (int)rintf(y); return (unsigned)q & 15u; }
; __device__ __forceinline__ void cvt_row_fp4(const float* __restrict__ src, unsigned char* __restrict__ T4, float* __restrict__ inv_scale, int e, int lane) {
;     f32x4 v[4]; float am = 0.f;
; #pragma unroll
;     for (int j = 0; j < 4; ++j) { v[j] = *(const f32x4*)(src + (size_t)e * 1024 + 16 * lane + 4 * j);
;         am = fmaxf(am, fmaxf(fmaxf(fabsf(v[j].x), fabsf(v[j].y)), fmaxf(fabsf(v[j].z), fabsf(v[j].w)))); }
; #pragma unroll
;     for (int o = 1; o < 64; o <<= 1) am = fmaxf(am, __shfl_xor(am, o));
;     const float sc = am > 0.f ? 7.f / am : 0.f;
;     unsigned n0 = 0u, n1 = 0u;
; #pragma unroll
;     for (int i = 0; i < 8; ++i) { n0 |= fp4_code(v[i >> 2][i & 3] * sc) << (4 * i); n1 |= fp4_code(v[2 + (i >> 2)][i & 3] * sc) << (4 * i); }
;     const unsigned p0 = (unsigned)__builtin_amdgcn_update_dpp(0, (int)n0, 0xB1, 0xf, 0xf, true), p1 = (unsigned)__builtin_amdgcn_update_dpp(0, (int)n1, 0xB1, 0xf, 0xf, true);
;     if ((lane & 1) == 0) {
.LBB0_462:
	s_add_i32 s0, s0, s10
	s_add_u32 s12, s12, s14
	s_addc_u32 s13, s13, s15
	v_lshl_add_u64 v[10:11], v[10:11], 0, s[16:17]
	s_cmpk_lt_i32 s0, 0x6400
	v_lshl_add_u64 v[12:13], v[12:13], 0, s[22:23]
	s_cbranch_scc0 .LBB0_472
.LBB0_463:
	s_cmpk_gt_i32 s0, 0x3fff
	s_mov_b64 s[40:41], -1
	s_cbranch_scc0 .LBB0_469
	s_add_i32 s8, s0, 0xffffc000
	s_waitcnt vmcnt(20)
	v_add_u32_e32 v46, s80, v44
	ds_read_b128 v[22:25], v46
	ds_read_b128 v[26:29], v46 offset:1024
	ds_read_b128 v[30:33], v46 offset:2048
	ds_read_b128 v[34:37], v46 offset:3072
	s_lshl_b32 s84, s10, 2
	s_add_i32 s84, s84, s0
	s_cmpk_lt_i32 s84, 0x6400
	s_cselect_b32 s84, s84, s0
	s_cmpk_lt_i32 s84, 0x4000
	s_cselect_b32 s86, s82, s24
	s_cselect_b32 s87, s83, s25
	s_and_b32 s85, s84, 0x3fff
	s_lshl_b32 s85, s85, 12
	s_add_u32 s86, s86, s85
	s_addc_u32 s87, s87, 0
	v_cmp_lt_i32_e32 vcc, v14, v7
	s_waitcnt lgkmcnt(0)
	s_mov_b32 m0, s80
	s_nop 0
	global_load_lds_dwordx4 v45, s[86:87]
	s_add_i32 m0, s80, 0x3f0
	s_nop 0
	global_load_lds_dwordx4 v45, s[86:87] offset:16
	s_add_i32 m0, s80, 0x7e0
	s_nop 0
	global_load_lds_dwordx4 v45, s[86:87] offset:32
	s_add_i32 m0, s80, 0xbd0
	s_nop 0
	global_load_lds_dwordx4 v45, s[86:87] offset:48
	s_add_i32 s80, s80, 0x1000
	s_sub_i32 s85, s80, s79
	s_and_b32 s85, s85, 0x3fff
	s_add_i32 s80, s79, s85
	v_max_f32_e64 v20, |v25|, |v25|
	v_max_f32_e64 v21, |v24|, |v24|
	v_max_f32_e64 v38, |v29|, |v29|
	v_max_f32_e64 v39, |v28|, |v28|
	v_max_f32_e64 v40, |v33|, |v33|
	v_max_f32_e64 v41, |v32|, |v32|
	v_max_f32_e64 v42, |v37|, |v37|
	v_max_f32_e64 v43, |v36|, |v36|
	v_max_f32_e32 v20, v21, v20
	v_max_f32_e32 v21, v39, v38
	v_max_f32_e32 v38, v41, v40
	v_max_f32_e32 v39, v43, v42
	v_max3_f32 v20, |v22|, |v23|, v20
	v_max3_f32 v21, |v26|, |v27|, v21
	v_cndmask_b32_e32 v2, v1, v14, vcc
	v_max3_f32 v38, |v30|, |v31|, v38
	v_max3_f32 v39, |v34|, |v35|, v39
	v_max3_f32 v20, v20, 0, v21
	v_lshlrev_b32_e32 v2, 2, v2
	v_max3_f32 v20, v20, v38, v39
	ds_bpermute_b32 v2, v2, v20
	v_cmp_lt_i32_e32 vcc, v15, v7
	s_waitcnt lgkmcnt(0)
	v_max_f32_e32 v2, v2, v2
	v_cndmask_b32_e32 v21, v1, v15, vcc
	v_lshlrev_b32_e32 v21, 2, v21
	v_max_f32_e32 v2, v20, v2
	ds_bpermute_b32 v20, v21, v2
	v_cmp_lt_i32_e32 vcc, v16, v7
	s_waitcnt lgkmcnt(0)
	v_max_f32_e32 v20, v20, v20
	v_cndmask_b32_e32 v21, v1, v16, vcc
	v_lshlrev_b32_e32 v21, 2, v21
	v_max_f32_e32 v2, v2, v20
	ds_bpermute_b32 v20, v21, v2
	v_cmp_lt_i32_e32 vcc, v17, v7
	s_waitcnt lgkmcnt(0)
	v_max_f32_e32 v20, v20, v20
	v_cndmask_b32_e32 v21, v1, v17, vcc
	v_lshlrev_b32_e32 v21, 2, v21
	v_max_f32_e32 v2, v2, v20
	ds_bpermute_b32 v20, v21, v2
	v_cmp_lt_i32_e32 vcc, v18, v7
	s_waitcnt lgkmcnt(0)
	v_max_f32_e32 v20, v20, v20
	v_cndmask_b32_e32 v21, v1, v18, vcc
	v_lshlrev_b32_e32 v21, 2, v21
	v_max_f32_e32 v2, v2, v20
	ds_bpermute_b32 v20, v21, v2
	v_cmp_lt_i32_e32 vcc, v19, v7
	s_waitcnt lgkmcnt(0)
	v_max_f32_e32 v20, v20, v20
	v_cndmask_b32_e32 v21, v1, v19, vcc
	v_lshlrev_b32_e32 v21, 2, v21
	v_max_f32_e32 v2, v2, v20
	ds_bpermute_b32 v20, v21, v2
	s_waitcnt lgkmcnt(0)
	v_max_f32_e32 v20, v20, v20
	v_max_f32_e32 v20, v2, v20
	v_div_scale_f32 v2, s[40:41], v20, v20, s1
	v_rcp_f32_e32 v21, v2
	v_div_scale_f32 v38, vcc, s1, v20, s1
	v_fma_f32 v39, -v2, v21, 1.0
	v_fmac_f32_e32 v21, v39, v21
	v_mul_f32_e32 v39, v38, v21
	v_fma_f32 v40, -v2, v39, v38
	v_fmac_f32_e32 v39, v40, v21
	v_fma_f32 v2, -v2, v39, v38
	v_div_fmas_f32 v2, v2, v21, v39
	v_div_fixup_f32 v2, v2, v20, s1
	v_cmp_lt_f32_e32 vcc, 0, v20
	s_nop 1
	v_cndmask_b32_e32 v2, 0, v2, vcc
	v_mul_f32_e32 v21, v22, v2
	v_mul_f32_e32 v22, v30, v2
	v_mul_f32_e32 v23, v23, v2
	v_mul_f32_e32 v30, v31, v2
	v_mul_f32_e32 v31, v32, v2
	v_mul_f32_e32 v25, v25, v2
	v_mul_f32_e32 v32, v33, v2
	v_mul_f32_e32 v26, v26, v2
	v_mul_f32_e32 v33, v34, v2
	v_mul_f32_e32 v27, v27, v2
	v_mul_f32_e32 v34, v35, v2
	v_mul_f32_e32 v24, v24, v2
	v_mul_f32_e32 v28, v28, v2
	v_mul_f32_e32 v35, v36, v2
	v_mul_f32_e32 v29, v29, v2
	v_mul_f32_e32 v2, v37, v2
	v_rndne_f32_e32 v21, v21
	v_rndne_f32_e32 v22, v22
	v_rndne_f32_e32 v23, v23
	v_rndne_f32_e32 v30, v30
	v_rndne_f32_e32 v25, v25
	v_rndne_f32_e32 v32, v32
	v_rndne_f32_e32 v26, v26
	v_rndne_f32_e32 v27, v27
	v_rndne_f32_e32 v34, v34
	v_rndne_f32_e32 v24, v24
	v_rndne_f32_e32 v29, v29
	v_rndne_f32_e32 v2, v2
	v_cvt_i32_f32_e32 v21, v21
	v_cvt_i32_f32_e32 v22, v22
	v_cvt_i32_f32_e32 v23, v23
	v_cvt_i32_f32_e32 v30, v30
	v_cvt_i32_f32_e32 v25, v25
	v_cvt_i32_f32_e32 v32, v32
	v_cvt_i32_f32_sdwa v36, v26 dst_sel:WORD_1 dst_unused:UNUSED_PAD src0_sel:DWORD
	v_cvt_i32_f32_e32 v26, v27
	v_cvt_i32_f32_e32 v27, v34
	v_rndne_f32_e32 v31, v31
	v_rndne_f32_e32 v33, v33
	v_rndne_f32_e32 v28, v28
	v_rndne_f32_e32 v35, v35
	v_cvt_i32_f32_e32 v24, v24
	v_cvt_i32_f32_e32 v29, v29
	v_cvt_i32_f32_e32 v2, v2
	v_cvt_i32_f32_e32 v31, v31
	v_cvt_i32_f32_sdwa v33, v33 dst_sel:WORD_1 dst_unused:UNUSED_PAD src0_sel:DWORD
	v_cvt_i32_f32_sdwa v28, v28 dst_sel:BYTE_3 dst_unused:UNUSED_PAD src0_sel:DWORD
	v_cvt_i32_f32_sdwa v34, v35 dst_sel:BYTE_3 dst_unused:UNUSED_PAD src0_sel:DWORD
	v_and_b32_e32 v21, 15, v21
	v_and_b32_e32 v22, 15, v22
	v_lshlrev_b32_e32 v23, 4, v23
	v_lshlrev_b32_e32 v30, 4, v30
	v_lshlrev_b32_e32 v35, 12, v25
	v_lshlrev_b32_e32 v32, 12, v32
	v_lshlrev_b32_e32 v26, 20, v26
	v_lshlrev_b32_e32 v27, 20, v27
	v_lshlrev_b32_e32 v24, 8, v24
	v_lshlrev_b32_e32 v29, 28, v29
	v_lshlrev_b32_e32 v37, 28, v2
	v_and_or_b32 v25, v23, s3, v21
	v_and_or_b32 v2, v30, s3, v22
	v_and_b32_e32 v22, 0xf000, v35
	v_and_b32_e32 v23, 0xf000, v32
	v_and_b32_e32 v30, 0xf00000, v26
	v_and_b32_e32 v32, 0xf00000, v27
	v_lshlrev_b32_e32 v31, 8, v31
	v_and_or_b32 v26, v28, s34, v29
	v_and_or_b32 v21, v34, s34, v37
	v_and_or_b32 v29, v24, s11, v22
	v_and_or_b32 v27, v36, s19, v30
	v_and_or_b32 v22, v33, s19, v32
	v_and_or_b32 v24, v31, s11, v23
	v_or_b32_e32 v23, v27, v26
	v_or_b32_e32 v28, v22, v21
	v_or3_b32 v23, v23, v25, v29
	v_or3_b32 v30, v28, v2, v24
	s_nop 0
	v_mov_b32_dpp v28, v23 quad_perm:[1,0,3,2] row_mask:0xf bank_mask:0xf bound_ctrl:1
	v_mov_b32_dpp v23, v30 quad_perm:[1,0,3,2] row_mask:0xf bank_mask:0xf bound_ctrl:1
	s_and_saveexec_b64 s[40:41], s[4:5]
	s_cbranch_execz .LBB0_466
; __device__ __forceinline__ void cvt_row_fp4(const float* __restrict__ src, unsigned char* __restrict__ T4, float* __restrict__ inv_scale, int e, int lane) {
;     ...
;     if ((lane & 1) == 0) {
;         v4u o;
;         o.x = spread4(n0) | (spread4(p0) << 4); o.y = spread4(n0 >> 16) | (spread4(p0 >> 16) << 4);
;         o.z = spread4(n1) | (spread4(p1) << 4); o.w = spread4(n1 >> 16) | (spread4(p1 >> 16) << 4);
;         *(v4u*)(T4 + ((size_t)(lane >> 4) * 16384 + e) * 128 + 16 * ((lane & 15) >> 1)) = o;
;     }
;     if (lane == 0) inv_scale[e] = am * (1.f / (7.f * 16.f));
	v_lshl_or_b32 v25, v29, 8, v25
	v_perm_b32 v29, v28, v28, s35
	v_lshlrev_b32_e32 v30, 4, v29
	v_lshl_or_b32 v25, v25, 4, v25
	v_lshl_or_b32 v29, v29, 8, v30
	v_bfi_b32 v30, s42, v25, v29
	v_lshrrev_b32_e32 v25, 8, v26
	v_lshrrev_b32_e32 v26, 16, v28
	v_or_b32_sdwa v25, v25, v27 dst_sel:DWORD dst_unused:UNUSED_PAD src0_sel:DWORD src1_sel:WORD_1
	v_lshlrev_b32_e32 v27, 8, v26
	v_bitop3_b32 v26, v27, s43, v26 bitop3:0xc8
	v_lshlrev_b32_e32 v27, 4, v26
	v_lshl_or_b32 v25, v25, 4, v25
	v_lshl_or_b32 v26, v26, 8, v27
	v_lshl_or_b32 v2, v24, 8, v2
	v_perm_b32 v24, v23, v23, s35
	v_bfi_b32 v31, s42, v25, v26
	v_lshlrev_b32_e32 v25, 4, v24
	v_lshl_or_b32 v2, v2, 4, v2
	v_lshl_or_b32 v24, v24, 8, v25
	v_bfi_b32 v32, s42, v2, v24
	v_lshrrev_b32_e32 v2, 8, v21
	v_lshrrev_b32_e32 v21, 16, v23
	v_or_b32_sdwa v2, v2, v22 dst_sel:DWORD dst_unused:UNUSED_PAD src0_sel:DWORD src1_sel:WORD_1
	v_lshlrev_b32_e32 v22, 8, v21
	v_bitop3_b32 v21, v22, s43, v21 bitop3:0xc8
	v_lshlrev_b32_e32 v22, 4, v21
	v_lshl_or_b32 v2, v2, 4, v2
	v_lshl_or_b32 v21, v21, 8, v22
	v_bfi_b32 v33, s42, v2, v21
	v_add_u32_e32 v2, s8, v6
	v_lshlrev_b64 v[22:23], 7, v[2:3]
	v_lshl_add_u64 v[22:23], v[8:9], 0, v[22:23]
	global_store_dwordx4 v[22:23], v[30:33], off

; __device__ __forceinline__ void cvt_row_i4(const float* __restrict__ src, unsigned char* __restrict__ T4, float* __restrict__ inv_scale, int e, int lane) {
;     f32x4 v[4]; float am = 0.f;
; #pragma unroll
;     for (int j = 0; j < 4; ++j) { v[j] = *(const f32x4*)(src + (size_t)e * 1024 + 16 * lane + 4 * j);
;         am = fmaxf(am, fmaxf(fmaxf(fabsf(v[j].x), fabsf(v[j].y)), fmaxf(fabsf(v[j].z), fabsf(v[j].w)))); }
; #pragma unroll
;     for (int o = 1; o < 64; o <<= 1) am = fmaxf(am, __shfl_xor(am, o));
;     const float sc = am > 0.f ? 7.f / am : 0.f;
;     v2u o;
; #pragma unroll
;     for (int k = 0; k < 2; ++k) { unsigned w = 0u;
; #pragma unroll
;         for (int i = 0; i < 8; ++i) { const int q = (int)rintf(v[2 * k + (i >> 2)][i & 3] * sc); w |= ((unsigned)q & 15u) << (4 * i); }
;         o[k] = w; }
;     *(v2u*)(T4 + ((size_t)(lane >> 4) * 16384 + e) * 128 + 8 * (lane & 15)) = o;
;     if (lane == 0) inv_scale[e] = am * (1.f / 7.f);
.LBB0_469:
	s_and_b64 vcc, exec, s[40:41]
	s_cbranch_vccz .LBB0_462
	s_waitcnt vmcnt(20)
	v_add_u32_e32 v46, s80, v44
	ds_read_b128 v[20:23], v46
	ds_read_b128 v[24:27], v46 offset:1024
	ds_read_b128 v[28:31], v46 offset:2048
	ds_read_b128 v[32:35], v46 offset:3072
	s_lshl_b32 s84, s10, 2
	s_add_i32 s84, s84, s0
	s_cmpk_lt_i32 s84, 0x6400
	s_cselect_b32 s84, s84, s0
	s_cmpk_lt_i32 s84, 0x4000
	s_cselect_b32 s86, s82, s24
	s_cselect_b32 s87, s83, s25
	s_and_b32 s85, s84, 0x3fff
	s_lshl_b32 s85, s85, 12
	s_add_u32 s86, s86, s85
	s_addc_u32 s87, s87, 0
	v_cmp_lt_i32_e32 vcc, v14, v7
	s_waitcnt lgkmcnt(0)
	s_mov_b32 m0, s80
	s_nop 0
	global_load_lds_dwordx4 v45, s[86:87]
	s_add_i32 m0, s80, 0x3f0
	s_nop 0
	global_load_lds_dwordx4 v45, s[86:87] offset:16
	s_add_i32 m0, s80, 0x7e0
	s_nop 0
	global_load_lds_dwordx4 v45, s[86:87] offset:32
	s_add_i32 m0, s80, 0xbd0
	s_nop 0
	global_load_lds_dwordx4 v45, s[86:87] offset:48
	s_add_i32 s80, s80, 0x1000
	s_sub_i32 s85, s80, s79
	s_and_b32 s85, s85, 0x3fff
	s_add_i32 s80, s79, s85
	v_max_f32_e64 v36, |v23|, |v23|
	v_max_f32_e64 v37, |v22|, |v22|
	v_max_f32_e64 v38, |v27|, |v27|
	v_max_f32_e64 v39, |v26|, |v26|
	v_max_f32_e64 v40, |v31|, |v31|
	v_max_f32_e64 v41, |v30|, |v30|
	v_max_f32_e64 v42, |v35|, |v35|
	v_max_f32_e64 v43, |v34|, |v34|
	v_max_f32_e32 v36, v37, v36
	v_max_f32_e32 v37, v39, v38
	v_max_f32_e32 v38, v41, v40
	v_max_f32_e32 v39, v43, v42
	v_max3_f32 v36, |v20|, |v21|, v36
	v_max3_f32 v37, |v24|, |v25|, v37
	v_cndmask_b32_e32 v2, v1, v14, vcc
	v_max3_f32 v38, |v28|, |v29|, v38
	v_max3_f32 v39, |v32|, |v33|, v39
	v_max3_f32 v36, v36, 0, v37
	v_lshlrev_b32_e32 v2, 2, v2
	v_max3_f32 v36, v36, v38, v39
	ds_bpermute_b32 v2, v2, v36
	v_cmp_lt_i32_e32 vcc, v15, v7
	s_waitcnt lgkmcnt(0)
	v_max_f32_e32 v2, v2, v2
	v_cndmask_b32_e32 v37, v1, v15, vcc
	v_lshlrev_b32_e32 v37, 2, v37
	v_max_f32_e32 v2, v36, v2
	ds_bpermute_b32 v36, v37, v2
	v_cmp_lt_i32_e32 vcc, v16, v7
	s_waitcnt lgkmcnt(0)
	v_max_f32_e32 v36, v36, v36
	v_cndmask_b32_e32 v37, v1, v16, vcc
	v_lshlrev_b32_e32 v37, 2, v37
	v_max_f32_e32 v2, v2, v36
	ds_bpermute_b32 v36, v37, v2
	v_cmp_lt_i32_e32 vcc, v17, v7
	s_waitcnt lgkmcnt(0)
	v_max_f32_e32 v36, v36, v36
	v_cndmask_b32_e32 v37, v1, v17, vcc
	v_lshlrev_b32_e32 v37, 2, v37
	v_max_f32_e32 v2, v2, v36
	ds_bpermute_b32 v36, v37, v2
	v_cmp_lt_i32_e32 vcc, v18, v7
	s_waitcnt lgkmcnt(0)
	v_max_f32_e32 v36, v36, v36
	v_cndmask_b32_e32 v37, v1, v18, vcc
	v_lshlrev_b32_e32 v37, 2, v37
	v_max_f32_e32 v2, v2, v36
	ds_bpermute_b32 v36, v37, v2
	v_cmp_lt_i32_e32 vcc, v19, v7
	s_waitcnt lgkmcnt(0)
	v_max_f32_e32 v36, v36, v36
	v_cndmask_b32_e32 v37, v1, v19, vcc
	v_lshlrev_b32_e32 v37, 2, v37
	v_max_f32_e32 v2, v2, v36
	ds_bpermute_b32 v36, v37, v2
	s_waitcnt lgkmcnt(0)
	v_max_f32_e32 v36, v36, v36
	v_max_f32_e32 v2, v2, v36
	v_div_scale_f32 v36, s[40:41], v2, v2, s1
	v_rcp_f32_e32 v37, v36
	v_div_scale_f32 v38, vcc, s1, v2, s1
	v_fma_f32 v39, -v36, v37, 1.0
	v_fmac_f32_e32 v37, v39, v37
	v_mul_f32_e32 v39, v38, v37
	v_fma_f32 v40, -v36, v39, v38
	v_fmac_f32_e32 v39, v40, v37
	v_fma_f32 v36, -v36, v39, v38
	v_div_fmas_f32 v36, v36, v37, v39
	v_div_fixup_f32 v36, v36, v2, s1
	v_cmp_lt_f32_e32 vcc, 0, v2
	s_nop 1
	v_cndmask_b32_e32 v36, 0, v36, vcc
	v_mul_f32_e32 v20, v20, v36
	v_mul_f32_e32 v21, v21, v36
	v_mul_f32_e32 v22, v22, v36
	v_mul_f32_e32 v28, v28, v36
	v_mul_f32_e32 v29, v29, v36
	v_mul_f32_e32 v30, v30, v36
	v_mul_f32_e32 v23, v23, v36
	v_mul_f32_e32 v27, v27, v36
	v_mul_f32_e32 v31, v31, v36
	v_mul_f32_e32 v35, v35, v36
	v_rndne_f32_e32 v20, v20
	v_rndne_f32_e32 v21, v21
	v_rndne_f32_e32 v22, v22
	v_rndne_f32_e32 v28, v28
	v_rndne_f32_e32 v29, v29
	v_rndne_f32_e32 v30, v30
	v_mul_f32_e32 v24, v24, v36
	v_mul_f32_e32 v25, v25, v36
	v_mul_f32_e32 v32, v32, v36
	v_mul_f32_e32 v33, v33, v36
	v_rndne_f32_e32 v23, v23
	v_rndne_f32_e32 v27, v27
	v_rndne_f32_e32 v31, v31
	v_rndne_f32_e32 v35, v35
	v_cvt_i32_f32_e32 v20, v20
	v_cvt_i32_f32_e32 v21, v21
	v_cvt_i32_f32_e32 v22, v22
	v_cvt_i32_f32_e32 v28, v28
	v_cvt_i32_f32_e32 v29, v29
	v_cvt_i32_f32_e32 v30, v30
	v_mul_f32_e32 v26, v26, v36
	v_mul_f32_e32 v34, v34, v36
	v_rndne_f32_e32 v24, v24
	v_rndne_f32_e32 v25, v25
	v_rndne_f32_e32 v32, v32
	v_rndne_f32_e32 v33, v33
	v_cvt_i32_f32_e32 v23, v23
	v_cvt_i32_f32_e32 v27, v27
	v_cvt_i32_f32_e32 v31, v31
	v_cvt_i32_f32_e32 v35, v35
	v_rndne_f32_e32 v26, v26
	v_rndne_f32_e32 v34, v34
	v_cvt_i32_f32_sdwa v24, v24 dst_sel:WORD_1 dst_unused:UNUSED_PAD src0_sel:DWORD
	v_cvt_i32_f32_e32 v25, v25
	v_cvt_i32_f32_sdwa v32, v32 dst_sel:WORD_1 dst_unused:UNUSED_PAD src0_sel:DWORD
	v_cvt_i32_f32_e32 v33, v33
	v_cvt_i32_f32_sdwa v26, v26 dst_sel:BYTE_3 dst_unused:UNUSED_PAD src0_sel:DWORD
	v_cvt_i32_f32_sdwa v34, v34 dst_sel:BYTE_3 dst_unused:UNUSED_PAD src0_sel:DWORD
	v_and_b32_e32 v20, 15, v20
	v_lshlrev_b32_e32 v21, 4, v21
	v_lshlrev_b32_e32 v22, 8, v22
	v_and_b32_e32 v28, 15, v28
	v_lshlrev_b32_e32 v29, 4, v29
	v_lshlrev_b32_e32 v30, 8, v30
	v_lshlrev_b32_e32 v23, 12, v23
	v_lshlrev_b32_e32 v31, 12, v31
	v_and_b32_e32 v21, 0xf0, v21
	v_and_b32_e32 v22, 0xf00, v22
	v_lshl_or_b32 v20, v27, 28, v20
	v_and_b32_e32 v27, 0xf0, v29
	v_and_b32_e32 v29, 0xf00, v30
	v_lshl_or_b32 v28, v35, 28, v28
	v_and_b32_e32 v24, 0xf0000, v24
	v_lshlrev_b32_e32 v25, 20, v25
	v_and_b32_e32 v32, 0xf0000, v32
	v_lshlrev_b32_e32 v33, 20, v33
	v_and_b32_e32 v23, 0xf000, v23
	v_and_b32_e32 v30, 0xf000, v31
	v_or3_b32 v20, v20, v21, v22
	v_or3_b32 v21, v28, v27, v29
	v_and_b32_e32 v26, 0xf000000, v26
	v_and_b32_e32 v34, 0xf000000, v34
	v_and_b32_e32 v25, 0xf00000, v25
	v_and_b32_e32 v31, 0xf00000, v33
	v_or3_b32 v20, v20, v23, v24
	v_or3_b32 v21, v21, v30, v32
	v_or3_b32 v20, v20, v25, v26
	v_or3_b32 v21, v21, v31, v34
	global_store_dwordx2 v[10:11], v[20:21], off
	s_and_saveexec_b64 s[40:41], s[6:7]
	s_cbranch_execz .LBB0_461
	v_mul_f32_e32 v2, 0x3e124925, v2
	global_store_dword v3, v2, s[12:13]
	s_branch .LBB0_461

; __global__ void __launch_bounds__(NTHR, 2) mega(Args args) {
;     ...
;         {
;             const int nextra = 288 > G ? 288 - G : 0, nslack = G - nextra;
;             if ((int)blockIdx.x >= nextra && rep == 0)
;                 for (int e = 2 * 16384 - CVT_LATE + ((int)blockIdx.x - nextra) * NWAVES + wave; e < 2 * 16384; e += nslack * NWAVES) peer::cvt_row_fp4(pv, VT8, SVs, e - 16384, lane);
;         }
.LBB0_537:
	s_sub_i32 s0, 0x120, s18
	s_cmpk_lt_i32 s18, 0x120
	s_cselect_b32 s0, s0, 0
	s_cmp_lt_i32 s2, s0
	s_cselect_b64 s[4:5], -1, 0
	s_sub_i32 s1, s2, s0
	s_lshl_b32 s1, s1, 3
	s_add_i32 s1, s77, s1
	s_add_i32 s3, s1, 0x6400
	s_cmpk_gt_i32 s3, 0x7fff
	s_cselect_b64 s[6:7], -1, 0
	s_or_b64 s[4:5], s[4:5], s[6:7]
	s_andn2_b64 vcc, exec, s[4:5]
	s_cbranch_vccz .LBB0_544
	v_and_b32_e32 v1, 1, v0
	v_cmp_eq_u32_e64 s[4:5], 0, v1
	v_mbcnt_lo_u32_b32 v1, -1, 0
	v_mbcnt_hi_u32_b32 v2, -1, v1
	v_and_b32_e32 v1, 64, v2
	v_add_u32_e32 v3, 64, v1
	v_xor_b32_e32 v1, 1, v2
	v_cmp_lt_i32_e32 vcc, v1, v3
	v_xor_b32_e32 v4, 2, v2
	s_add_i32 s3, s2, s18
	v_cndmask_b32_e32 v1, v2, v1, vcc
	v_cmp_lt_i32_e32 vcc, v4, v3
	s_lshl_b32 s3, s3, 3
	s_max_i32 s10, s18, 0x120
	v_cndmask_b32_e32 v4, v2, v4, vcc
	v_lshlrev_b32_e32 v8, 2, v4
	v_xor_b32_e32 v4, 4, v2
	v_cmp_lt_i32_e32 vcc, v4, v3
	s_add_i32 s3, s77, s3
	s_lshl_b32 s10, s10, 3
	v_cndmask_b32_e32 v4, v2, v4, vcc
	v_lshlrev_b32_e32 v9, 2, v4
	v_xor_b32_e32 v4, 8, v2
	v_cmp_lt_i32_e32 vcc, v4, v3
	s_add_i32 s16, s1, 0x2400
	s_sub_i32 s0, s18, s0
	v_cndmask_b32_e32 v4, v2, v4, vcc
	v_lshlrev_b32_e32 v10, 2, v4
	v_xor_b32_e32 v4, 16, v2
	v_cmp_lt_i32_e32 vcc, v4, v3
	s_sub_i32 s3, s3, s10
	s_ashr_i32 s17, s16, 31
	v_cndmask_b32_e32 v4, v2, v4, vcc
	s_lshl_b32 s0, s0, 3
	v_lshlrev_b32_e32 v11, 2, v4
	v_xor_b32_e32 v4, 32, v2
	s_addk_i32 s3, 0x6400
	s_lshl_b64 s[10:11], s[16:17], 2
	v_cmp_lt_i32_e32 vcc, v4, v3
	s_add_u32 s1, s30, s10
	s_addc_u32 s11, s31, s11
	v_cndmask_b32_e32 v2, v2, v4, vcc
	v_lshlrev_b32_e32 v12, 2, v2
	s_add_u32 s10, s1, 0x3100000
	v_lshlrev_b32_e32 v2, 17, v0
	s_addc_u32 s11, s11, 0
	v_and_b32_e32 v2, 0x600000, v2
	v_mov_b32_e32 v3, 0
	s_lshl_b64 s[14:15], s[16:17], 7
	v_lshlrev_b32_e32 v6, 3, v0
	v_lshl_add_u64 v[4:5], v[2:3], 0, s[14:15]
	s_movk_i32 s14, 0x70
	v_and_or_b32 v4, v6, s14, v4
	s_ashr_i32 s1, s0, 31
	v_lshl_add_u64 v[4:5], s[30:31], 0, v[4:5]
	s_mov_b64 s[14:15], 0x2000000
	s_lshl_b64 s[12:13], s[0:1], 2
	v_lshl_add_u64 v[4:5], v[4:5], 0, s[14:15]
	s_lshl_b64 s[14:15], s[0:1], 7
	s_lshl_b64 s[16:17], s[16:17], 12
	s_add_u32 s16, s24, s16
	v_lshlrev_b32_e32 v2, 6, v178
	s_addc_u32 s17, s25, s17
	v_lshl_add_u64 v[6:7], s[16:17], 0, v[2:3]
	v_cmp_eq_u32_e64 s[6:7], 0, v178
	v_lshlrev_b32_e32 v1, 2, v1
	v_lshl_add_u64 v[6:7], v[6:7], 0, 32
	s_lshl_b64 s[16:17], s[0:1], 12
	s_mov_b32 s1, 0x40e00000
	s_movk_i32 s19, 0xf0
	s_movk_i32 s24, 0xf00
	s_mov_b32 s25, 0xf0000
	s_mov_b32 s34, 0xf000000
	s_mov_b32 s35, 0xc050c00
	s_mov_b32 s40, 0xf0f0f0f
	s_mov_b32 s41, 0xff00ff
	s_branch .LBB0_540
